# v39 plus weight-conversion tile loads issued back to back (one wait per tile instead of 16 round trips)
# speedup vs baseline: 1.0225x; 1.0225x over previous
; #define LAS __attribute__((address_space(3)))
; __device__ __forceinline__ void wconv_commit(const f32x4 (&v)[8], LAS float* tile) {
;     const int tid = threadIdx.x;
; #pragma unroll
;     for (int i = 0; i < 8; ++i) {
;         const int idx = tid + i * 512, kk = idx >> 6, c4 = (idx & 63) * 4;
;         tile[kk * 257 + c4 + 0] = v[i][0]; tile[kk * 257 + c4 + 1] = v[i][1]; tile[kk * 257 + c4 + 2] = v[i][2]; tile[kk * 257 + c4 + 3] = v[i][3];
;     }
; }
; __device__ __forceinline__ WItem p0_witem(int it, const float* const* in, unsigned char* ws) {
;     if (it < 2112) return ffn_witem(it, in[2], in[3], in[4], ws, nullptr);
;     WItem t; t.kind = 0; t.gk = nullptr;
;     if (it < 2976) { const int r = it - 2112, kt = r / 27, nt = r % 27; t.gk = in[5]; t.src = in[6]; t.dst = (bf16_t*)(ws + WS_WINT); t.ld = DIN; t.ncols = DIN; t.k0 = kt * 64; t.n0 = nt * 256; t.Kd = DM; t.kind = 3; }
;     else if (it < 3232) { const int r = it - 2976, kt = r >> 3, nt = r & 7; t.src = in[14]; t.dst = (bf16_t*)(ws + WS_WOUTT); t.ld = DM; t.ncols = DM; t.k0 = kt * 64; t.n0 = nt * 256; t.Kd = DM; }
;     else if (it < 3296) { const int r = it - 3232; t.src = in[9]; t.dst = (bf16_t*)(ws + WS_CW1KT); t.ld = 128; t.ncols = 128; t.k0 = r * 64; t.n0 = 0; t.Kd = 4096; t.kind = 4; }
;     else if (it < 3360) { const int r = it - 3296; t.src = in[12]; t.dst = (bf16_t*)(ws + WS_CW1VT); t.ld = 128; t.ncols = 128; t.k0 = r * 64; t.n0 = 0; t.Kd = 4096; t.kind = 4; }
;     else if (it < 3362) { const int r = it - 3360; t.src = in[10]; t.dst = (bf16_t*)(ws + WS_CW2KT); t.ld = 128; t.ncols = 128; t.k0 = r * 64; t.n0 = 0; t.Kd = 128; }
;     else { const int r = it - 3362; t.src = in[13]; t.dst = (bf16_t*)(ws + WS_CW2VT); t.ld = 128; t.ncols = 128; t.k0 = r * 64; t.n0 = 0; t.Kd = 128; }
;     return t;
.LBB0_63:
	s_add_i32 s37, s38, s28
	s_cmpk_gt_i32 s37, 0xd23
	s_cselect_b64 s[78:79], -1, 0
	s_and_b64 vcc, exec, s[78:79]
	s_waitcnt vmcnt(0)
	ds_write2_b32 v69, v0, v1 offset1:1
	ds_write2_b32 v69, v2, v3 offset0:2 offset1:3
	ds_write2_b32 v70, v4, v5 offset1:1
	ds_write2_b32 v70, v6, v7 offset0:2 offset1:3
	ds_write2_b32 v71, v8, v9 offset1:1
	ds_write2_b32 v72, v10, v11 offset1:1
	ds_write2_b32 v73, v12, v13 offset1:1
	ds_write2_b32 v73, v14, v15 offset0:2 offset1:3
	ds_write2_b32 v74, v16, v17 offset1:1
	ds_write2_b32 v75, v18, v19 offset1:1
	ds_write2_b32 v76, v20, v21 offset1:1
	ds_write2_b32 v76, v22, v23 offset0:2 offset1:3
	ds_write2_b32 v77, v24, v25 offset1:1
	ds_write2_b32 v78, v26, v27 offset1:1
	ds_write2_b32 v79, v28, v29 offset1:1
	ds_write2_b32 v79, v30, v31 offset0:2 offset1:3
	s_waitcnt lgkmcnt(0)
	s_barrier
	s_cbranch_vccnz .LBB0_124
	s_cmpk_gt_i32 s37, 0x83f
	s_mov_b64 s[4:5], -1
	s_cbranch_scc0 .LBB0_86
	s_cmpk_gt_u32 s37, 0xb9f
	s_cbranch_scc0 .LBB0_71
	s_cmpk_gt_u32 s37, 0xc9f
	s_cbranch_scc0 .LBB0_72
	s_cmpk_gt_u32 s37, 0xcdf
	s_cbranch_scc0 .LBB0_74
	s_cmpk_gt_u32 s37, 0xd1f
	s_cbranch_scc0 .LBB0_75
	s_cmpk_gt_u32 s37, 0xd21
	s_cbranch_scc0 .LBB0_76
	v_readlane_b32 s12, v254, 4
	s_lshl_b32 s4, s37, 6
	v_readlane_b32 s22, v254, 14
	v_readlane_b32 s23, v254, 15
	s_add_i32 s82, s4, 0xfffcb780
	v_readlane_b32 s13, v254, 5
	v_readlane_b32 s14, v254, 6
	v_readlane_b32 s15, v254, 7
	v_readlane_b32 s16, v254, 8
	v_readlane_b32 s17, v254, 9
	v_readlane_b32 s18, v254, 10
	v_readlane_b32 s19, v254, 11
	v_readlane_b32 s20, v254, 12
	v_readlane_b32 s21, v254, 13
	v_readlane_b32 s24, v254, 16
	v_readlane_b32 s25, v254, 17
	v_readlane_b32 s26, v254, 18
	v_readlane_b32 s27, v254, 19
	s_mov_b64 s[80:81], s[22:23]
	s_cbranch_execz .LBB0_77
	s_branch .LBB0_78

; template <bool NT = false>
; __device__ __forceinline__ void wconv_load(const WItem& t, f32x4 (&v)[8]) {
;     const int tid = threadIdx.x;
; #pragma unroll
;     for (int i = 0; i < 8; ++i) {
;         const int idx = tid + i * 512, kk = idx >> 6, c4 = (idx & 63) * 4;
;         v[i] = (f32x4){0.f, 0.f, 0.f, 0.f};
;         if (t.n0 + c4 + 3 < t.ncols) { const f32x4* sp = (const f32x4*)(t.src + (size_t)(t.k0 + kk) * t.ld + t.n0 + c4); v[i] = NT ? __builtin_nontemporal_load(sp) : *sp; }
;         if (t.gk) v[i] = v[i] * t.gk[t.k0 + kk];
;     }
; }
.LBB0_92:
	v_add_u32_e32 v0, s84, v52
	v_cmp_gt_i32_e64 s[4:5], s39, v0
	v_add_u32_e32 v98, s82, v168
	v_lshlrev_b32_e32 v38, 2, v41
	v_mov_b32_e32 v0, 0
	v_mov_b32_e32 v1, 0
	v_mov_b32_e32 v2, 0
	v_mov_b32_e32 v3, 0
	v_mov_b32_e32 v4, 0
	v_mov_b32_e32 v5, 0
	v_mov_b32_e32 v6, 0
	v_mov_b32_e32 v7, 0
	v_mov_b32_e32 v8, 0
	v_mov_b32_e32 v9, 0
	v_mov_b32_e32 v10, 0
	v_mov_b32_e32 v11, 0
	v_mov_b32_e32 v12, 0
	v_mov_b32_e32 v13, 0
	v_mov_b32_e32 v14, 0
	v_mov_b32_e32 v15, 0
	v_mov_b32_e32 v16, 0
	v_mov_b32_e32 v17, 0
	v_mov_b32_e32 v18, 0
	v_mov_b32_e32 v19, 0
	v_mov_b32_e32 v20, 0
	v_mov_b32_e32 v21, 0
	v_mov_b32_e32 v22, 0
	v_mov_b32_e32 v23, 0
	v_mov_b32_e32 v24, 0
	v_mov_b32_e32 v25, 0
	v_mov_b32_e32 v26, 0
	v_mov_b32_e32 v27, 0
	v_mov_b32_e32 v28, 0
	v_mov_b32_e32 v29, 0
	v_mov_b32_e32 v30, 0
	v_mov_b32_e32 v31, 0
	v_lshlrev_b32_e64 v100, 5, s39
	v_mov_b32_e32 v101, 0
	v_mov_b32_e32 v99, 0
	s_and_saveexec_b64 s[6:7], s[4:5]
	s_cbranch_execz .Lw0_ld_done
	v_mad_u64_u32 v[96:97], s[8:9], v98, s39, 0
	v_lshl_add_u64 v[96:97], v[96:97], 2, s[80:81]
	s_ashr_i32 s85, s84, 31
	v_lshl_add_u64 v[96:97], s[84:85], 2, v[96:97]
	v_lshl_add_u64 v[96:97], v[96:97], 0, v[38:39]
	global_load_dwordx4 v[0:3], v[96:97], off
	v_lshl_add_u64 v[96:97], v[96:97], 0, v[100:101]
	global_load_dwordx4 v[4:7], v[96:97], off
	v_lshl_add_u64 v[96:97], v[96:97], 0, v[100:101]
	global_load_dwordx4 v[8:11], v[96:97], off
	v_lshl_add_u64 v[96:97], v[96:97], 0, v[100:101]
	global_load_dwordx4 v[12:15], v[96:97], off
	v_lshl_add_u64 v[96:97], v[96:97], 0, v[100:101]
	global_load_dwordx4 v[16:19], v[96:97], off
	v_lshl_add_u64 v[96:97], v[96:97], 0, v[100:101]
	global_load_dwordx4 v[20:23], v[96:97], off
	v_lshl_add_u64 v[96:97], v[96:97], 0, v[100:101]
	global_load_dwordx4 v[24:27], v[96:97], off
	v_lshl_add_u64 v[96:97], v[96:97], 0, v[100:101]
	global_load_dwordx4 v[28:31], v[96:97], off
.Lw0_ld_done:
	s_or_b64 exec, exec, s[6:7]
	s_cmp_eq_u64 s[86:87], 0
	s_cbranch_scc1 .LBB0_124
	v_lshl_add_u64 v[102:103], v[98:99], 2, s[86:87]
	global_load_dword v104, v[102:103], off
	global_load_dword v105, v[102:103], off offset:32
	global_load_dword v106, v[102:103], off offset:64
	global_load_dword v107, v[102:103], off offset:96
	global_load_dword v108, v[102:103], off offset:128
	global_load_dword v109, v[102:103], off offset:160
	global_load_dword v110, v[102:103], off offset:192
	global_load_dword v111, v[102:103], off offset:224
	s_waitcnt vmcnt(0)
	v_mul_f32_e32 v0, v104, v0
	v_mul_f32_e32 v1, v104, v1
	v_mul_f32_e32 v2, v104, v2
	v_mul_f32_e32 v3, v104, v3
	v_mul_f32_e32 v4, v105, v4
	v_mul_f32_e32 v5, v105, v5
	v_mul_f32_e32 v6, v105, v6
	v_mul_f32_e32 v7, v105, v7
	v_mul_f32_e32 v8, v106, v8
	v_mul_f32_e32 v9, v106, v9
	v_mul_f32_e32 v10, v106, v10
	v_mul_f32_e32 v11, v106, v11
	v_mul_f32_e32 v12, v107, v12
	v_mul_f32_e32 v13, v107, v13
	v_mul_f32_e32 v14, v107, v14
	v_mul_f32_e32 v15, v107, v15
	v_mul_f32_e32 v16, v108, v16
	v_mul_f32_e32 v17, v108, v17
	v_mul_f32_e32 v18, v108, v18
	v_mul_f32_e32 v19, v108, v19
	v_mul_f32_e32 v20, v109, v20
	v_mul_f32_e32 v21, v109, v21
	v_mul_f32_e32 v22, v109, v22
	v_mul_f32_e32 v23, v109, v23
	v_mul_f32_e32 v24, v110, v24
	v_mul_f32_e32 v25, v110, v25
	v_mul_f32_e32 v26, v110, v26
	v_mul_f32_e32 v27, v110, v27
	v_mul_f32_e32 v28, v111, v28
	v_mul_f32_e32 v29, v111, v29
	v_mul_f32_e32 v30, v111, v30
	v_mul_f32_e32 v31, v111, v31

; #define LAS __attribute__((address_space(3)))
; __device__ __forceinline__ void wconv_commit(const f32x4 (&v)[8], LAS float* tile) {
;     const int tid = threadIdx.x;
; #pragma unroll
;     for (int i = 0; i < 8; ++i) {
;         const int idx = tid + i * 512, kk = idx >> 6, c4 = (idx & 63) * 4;
;         tile[kk * 257 + c4 + 0] = v[i][0]; tile[kk * 257 + c4 + 1] = v[i][1]; tile[kk * 257 + c4 + 2] = v[i][2]; tile[kk * 257 + c4 + 3] = v[i][3];
;     }
; }
; __global__ void __launch_bounds__(512, 2) mk_fwd(Args a) {
;     ...
;               for (int j = 0; j < nit; ++j) { wconv_commit(v, tile); __syncthreads(); if (j + 1 < nit) wconv_load<true>(ffn_witem(MK_WIDX(j + 1), a.in[16], a.in[17], a.in[18], ws, a.in[15]), v);
;                   wconv_drain<true>(ffn_witem(MK_WIDX(j), a.in[16], a.in[17], a.in[18], ws, a.in[15]), tile); __syncthreads(); }
.LBB0_790:
	s_add_i32 s33, s34, 1
	s_cmp_ge_u32 s33, s24
	s_waitcnt vmcnt(0)
	ds_write2_b32 v60, v0, v1 offset1:1
	ds_write2_b32 v60, v2, v3 offset0:2 offset1:3
	ds_write2_b32 v61, v4, v5 offset1:1
	ds_write2_b32 v61, v6, v7 offset0:2 offset1:3
	ds_write2_b32 v62, v8, v9 offset1:1
	ds_write2_b32 v63, v10, v11 offset1:1
	ds_write2_b32 v64, v12, v13 offset1:1
	ds_write2_b32 v64, v14, v15 offset0:2 offset1:3
	ds_write2_b32 v65, v16, v17 offset1:1
	ds_write2_b32 v66, v18, v19 offset1:1
	ds_write2_b32 v67, v20, v21 offset1:1
	ds_write2_b32 v67, v22, v23 offset0:2 offset1:3
	ds_write2_b32 v68, v24, v25 offset1:1
	ds_write2_b32 v69, v26, v27 offset1:1
	ds_write2_b32 v70, v28, v29 offset1:1
	ds_write2_b32 v70, v30, v31 offset0:2 offset1:3
	s_waitcnt lgkmcnt(0)
	s_barrier
	s_cbranch_scc1 .LBB0_831
	s_cmp_ge_u32 s33, s3
	s_mov_b64 s[4:5], -1
	s_cbranch_scc0 .LBB0_795
	s_add_i32 s6, s30, s22
	s_cbranch_execz .LBB0_796

; template <bool NT = false>
; __device__ __forceinline__ void wconv_load(const WItem& t, f32x4 (&v)[8]) {
;     const int tid = threadIdx.x;
; #pragma unroll
;     for (int i = 0; i < 8; ++i) {
;         const int idx = tid + i * 512, kk = idx >> 6, c4 = (idx & 63) * 4;
;         v[i] = (f32x4){0.f, 0.f, 0.f, 0.f};
;         if (t.n0 + c4 + 3 < t.ncols) { const f32x4* sp = (const f32x4*)(t.src + (size_t)(t.k0 + kk) * t.ld + t.n0 + c4); v[i] = NT ? __builtin_nontemporal_load(sp) : *sp; }
;         if (t.gk) v[i] = v[i] * t.gk[t.k0 + kk];
;     }
; }
.LBB0_799:
	v_or_b32_e32 v0, s14, v57
	v_cmp_gt_i32_e64 s[4:5], s35, v0
	v_add_u32_e32 v76, s18, v168
	v_mov_b32_e32 v37, v35
	v_mov_b32_e32 v0, 0
	v_mov_b32_e32 v1, 0
	v_mov_b32_e32 v2, 0
	v_mov_b32_e32 v3, 0
	v_mov_b32_e32 v4, 0
	v_mov_b32_e32 v5, 0
	v_mov_b32_e32 v6, 0
	v_mov_b32_e32 v7, 0
	v_mov_b32_e32 v8, 0
	v_mov_b32_e32 v9, 0
	v_mov_b32_e32 v10, 0
	v_mov_b32_e32 v11, 0
	v_mov_b32_e32 v12, 0
	v_mov_b32_e32 v13, 0
	v_mov_b32_e32 v14, 0
	v_mov_b32_e32 v15, 0
	v_mov_b32_e32 v16, 0
	v_mov_b32_e32 v17, 0
	v_mov_b32_e32 v18, 0
	v_mov_b32_e32 v19, 0
	v_mov_b32_e32 v20, 0
	v_mov_b32_e32 v21, 0
	v_mov_b32_e32 v22, 0
	v_mov_b32_e32 v23, 0
	v_mov_b32_e32 v24, 0
	v_mov_b32_e32 v25, 0
	v_mov_b32_e32 v26, 0
	v_mov_b32_e32 v27, 0
	v_mov_b32_e32 v28, 0
	v_mov_b32_e32 v29, 0
	v_mov_b32_e32 v30, 0
	v_mov_b32_e32 v31, 0
	v_lshlrev_b32_e64 v88, 5, s35
	v_mov_b32_e32 v89, 0
	v_mov_b32_e32 v77, 0
	s_and_saveexec_b64 s[6:7], s[4:5]
	s_cbranch_execz .Lw4_ld_done
	v_mad_i64_i32 v[74:75], s[8:9], v76, s35, 0
	v_lshl_add_u64 v[74:75], v[74:75], 2, s[16:17]
	s_ashr_i32 s15, s14, 31
	v_lshl_add_u64 v[74:75], s[14:15], 2, v[74:75]
	v_lshl_add_u64 v[74:75], v[74:75], 0, v[36:37]
	global_load_dwordx4 v[0:3], v[74:75], off nt
	v_lshl_add_u64 v[74:75], v[74:75], 0, v[88:89]
	global_load_dwordx4 v[4:7], v[74:75], off nt
	v_lshl_add_u64 v[74:75], v[74:75], 0, v[88:89]
	global_load_dwordx4 v[8:11], v[74:75], off nt
	v_lshl_add_u64 v[74:75], v[74:75], 0, v[88:89]
	global_load_dwordx4 v[12:15], v[74:75], off nt
	v_lshl_add_u64 v[74:75], v[74:75], 0, v[88:89]
	global_load_dwordx4 v[16:19], v[74:75], off nt
	v_lshl_add_u64 v[74:75], v[74:75], 0, v[88:89]
	global_load_dwordx4 v[20:23], v[74:75], off nt
	v_lshl_add_u64 v[74:75], v[74:75], 0, v[88:89]
	global_load_dwordx4 v[24:27], v[74:75], off nt
	v_lshl_add_u64 v[74:75], v[74:75], 0, v[88:89]
	global_load_dwordx4 v[28:31], v[74:75], off nt
.Lw4_ld_done:
	s_or_b64 exec, exec, s[6:7]
	s_cmp_eq_u64 s[12:13], 0
	s_cbranch_scc1 .LBB0_831
	v_lshl_add_u64 v[78:79], v[76:77], 2, s[12:13]
	global_load_dword v80, v[78:79], off
	global_load_dword v81, v[78:79], off offset:32
	global_load_dword v82, v[78:79], off offset:64
	global_load_dword v83, v[78:79], off offset:96
	global_load_dword v84, v[78:79], off offset:128
	global_load_dword v85, v[78:79], off offset:160
	global_load_dword v86, v[78:79], off offset:192
	global_load_dword v87, v[78:79], off offset:224
	s_waitcnt vmcnt(0)
	v_mul_f32_e32 v0, v80, v0
	v_mul_f32_e32 v1, v80, v1
	v_mul_f32_e32 v2, v80, v2
	v_mul_f32_e32 v3, v80, v3
	v_mul_f32_e32 v4, v81, v4
	v_mul_f32_e32 v5, v81, v5
	v_mul_f32_e32 v6, v81, v6
	v_mul_f32_e32 v7, v81, v7
	v_mul_f32_e32 v8, v82, v8
	v_mul_f32_e32 v9, v82, v9
	v_mul_f32_e32 v10, v82, v10
	v_mul_f32_e32 v11, v82, v11
	v_mul_f32_e32 v12, v83, v12
	v_mul_f32_e32 v13, v83, v13
	v_mul_f32_e32 v14, v83, v14
	v_mul_f32_e32 v15, v83, v15
	v_mul_f32_e32 v16, v84, v16
	v_mul_f32_e32 v17, v84, v17
	v_mul_f32_e32 v18, v84, v18
	v_mul_f32_e32 v19, v84, v19
	v_mul_f32_e32 v20, v85, v20
	v_mul_f32_e32 v21, v85, v21
	v_mul_f32_e32 v22, v85, v22
	v_mul_f32_e32 v23, v85, v23
	v_mul_f32_e32 v24, v86, v24
	v_mul_f32_e32 v25, v86, v25
	v_mul_f32_e32 v26, v86, v26
	v_mul_f32_e32 v27, v86, v27
	v_mul_f32_e32 v28, v87, v28
	v_mul_f32_e32 v29, v87, v29
	v_mul_f32_e32 v30, v87, v30
	v_mul_f32_e32 v31, v87, v31
